# w_in transpose: both 16-load halves of an item in flight together (on top of idle-time weight conversion)
# baseline (speedup 1.0000x reference)
; __device__ __forceinline__ void transpose_item(const float* __restrict__ W, int ld_src, int k0, int n0src, const float* __restrict__ kscale, bf16_t* __restrict__ WT, int ldt, int n0dst, LAS float* scr, int lane) {
; #pragma unroll 8
;     for (int i = 0; i < 32; ++i) { const int kk = 2 * i + (lane >> 5); float v = W[(size_t)(k0 + kk) * ld_src + n0src + (lane & 31)]; if (kscale) v *= kscale[k0 + kk]; scr[kk * 33 + (lane & 31)] = v; }
; __global__ void __launch_bounds__(512, 2) mk_fwd(Args args) {
;     ...
;             if (r < I_IN) { const int kb = r / 442, nb = r % 442, n0 = nb * 32;
;                 transpose_item(w_in + (size_t)L * DM * NIN, NIN, kb * 64, n0, nullptr, WIN + (size_t)L * NINP * DM, DM, n0 < NMIX ? n0 : n0 + (NMIXP - NMIX), scr, lane); continue; } r -= I_IN;
.LBB0_69:
	s_mul_hi_i32 s0, s36, 0x94458095
	s_add_i32 s0, s0, s36
	s_lshr_b32 s2, s0, 31
	s_ashr_i32 s0, s0, 8
	s_add_i32 s3, s0, s2
	s_mul_i32 s0, s3, 0x1ba
	s_sub_i32 s0, s36, s0
	s_lshl_b32 s2, s0, 5
	s_mul_i32 s14, s12, 0x6e80000
	s_mul_hi_i32 s13, s12, 0x6e80000
	s_add_u32 s15, s54, s14
	s_addc_u32 s13, s55, s13
	s_lshl_b32 s14, s3, 6
	s_ashr_i32 s3, s2, 31
	s_lshl_b64 s[36:37], s[2:3], 2
	s_add_u32 s36, s15, s36
	s_addc_u32 s37, s13, s37
	v_mov_b32_e32 v27, v5
	v_lshl_add_u64 v[28:29], s[36:37], 0, v[26:27]
	s_mov_b32 s3, s14
	s_mov_b32 s13, 1
	s_mov_b32 s15, 0
	s_mov_b32 s36, 32
	s_lshl_b32 s37, s13, 1
	s_lshl_b32 s38, s15, 1
	v_or_b32_e32 v4, s37, v1
	v_or_b32_e32 v27, s38, v2
	s_add_i32 s39, s37, 4
	s_add_i32 s40, s38, 4
	s_add_i32 s41, s37, 8
	s_add_i32 s42, s38, 8
	s_add_i32 s43, s37, 12
	s_add_i32 s44, s38, 12
	s_add_i32 s45, s37, 16
	s_add_i32 s46, s38, 16
	s_add_i32 s47, s37, 20
	s_add_i32 s48, s38, 20
	s_add_i32 s49, s37, 24
	s_add_i32 s50, s38, 24
	s_add_i32 s37, s37, 28
	s_add_i32 s38, s38, 28
	v_add_u32_e32 v30, s14, v27
	v_or_b32_e32 v63, s39, v1
	v_or_b32_e32 v78, s40, v2
	v_or_b32_e32 v79, s41, v1
	v_or_b32_e32 v80, s42, v2
	v_or_b32_e32 v81, s43, v1
	v_or_b32_e32 v82, s44, v2
	v_or_b32_e32 v83, s45, v1
	v_or_b32_e32 v84, s46, v2
	v_or_b32_e32 v85, s47, v1
	v_or_b32_e32 v86, s48, v2
	v_or_b32_e32 v87, s49, v1
	v_or_b32_e32 v88, s50, v2
	v_or_b32_e32 v89, s37, v1
	v_or_b32_e32 v90, s38, v2
	v_add_u32_e32 v32, s3, v4
	v_mad_i64_i32 v[30:31], s[38:39], v30, s35, v[28:29]
	v_add_u32_e32 v36, s3, v63
	v_add_u32_e32 v34, s14, v78
	v_add_u32_e32 v40, s3, v79
	v_add_u32_e32 v38, s14, v80
	v_add_u32_e32 v44, s3, v81
	v_add_u32_e32 v42, s14, v82
	v_add_u32_e32 v64, s3, v83
	v_add_u32_e32 v46, s14, v84
	v_add_u32_e32 v68, s3, v85
	v_add_u32_e32 v66, s14, v86
	v_add_u32_e32 v72, s3, v87
	v_add_u32_e32 v70, s14, v88
	v_add_u32_e32 v76, s3, v89
	v_add_u32_e32 v74, s14, v90
	v_mad_i64_i32 v[32:33], s[38:39], v32, s35, v[28:29]
	v_mad_i64_i32 v[34:35], s[38:39], v34, s35, v[28:29]
	v_mad_i64_i32 v[36:37], s[38:39], v36, s35, v[28:29]
	v_mad_i64_i32 v[38:39], s[38:39], v38, s35, v[28:29]
	v_mad_i64_i32 v[40:41], s[38:39], v40, s35, v[28:29]
	v_mad_i64_i32 v[42:43], s[38:39], v42, s35, v[28:29]
	v_mad_i64_i32 v[44:45], s[38:39], v44, s35, v[28:29]
	v_mad_i64_i32 v[46:47], s[38:39], v46, s35, v[28:29]
	v_mad_i64_i32 v[64:65], s[38:39], v64, s35, v[28:29]
	v_mad_i64_i32 v[66:67], s[38:39], v66, s35, v[28:29]
	v_mad_i64_i32 v[68:69], s[38:39], v68, s35, v[28:29]
	v_mad_i64_i32 v[70:71], s[38:39], v70, s35, v[28:29]
	v_mad_i64_i32 v[72:73], s[38:39], v72, s35, v[28:29]
	v_mad_i64_i32 v[74:75], s[38:39], v74, s35, v[28:29]
	v_mad_i64_i32 v[76:77], s[38:39], v76, s35, v[28:29]
	global_load_dword v91, v[30:31], off
	global_load_dword v92, v[32:33], off
	global_load_dword v93, v[34:35], off
	global_load_dword v94, v[36:37], off
	global_load_dword v95, v[38:39], off
	global_load_dword v96, v[40:41], off
	global_load_dword v97, v[42:43], off
	global_load_dword v98, v[44:45], off
	global_load_dword v99, v[46:47], off
	global_load_dword v100, v[64:65], off
	global_load_dword v101, v[66:67], off
	global_load_dword v102, v[68:69], off
	global_load_dword v103, v[70:71], off
	global_load_dword v104, v[72:73], off
	global_load_dword v105, v[74:75], off
	global_load_dword v106, v[76:77], off
	v_mad_u64_u32 v[30:31], s[38:39], v27, s18, v[12:13]
	v_mad_u64_u32 v[32:33], s[38:39], v4, s18, v[12:13]
	v_mad_u64_u32 v[34:35], s[38:39], v78, s18, v[12:13]
	v_mad_u64_u32 v[36:37], s[38:39], v63, s18, v[12:13]
	v_mad_u64_u32 v[38:39], s[38:39], v80, s18, v[12:13]
	v_mad_u64_u32 v[40:41], s[38:39], v79, s18, v[12:13]
	v_mad_u64_u32 v[42:43], s[38:39], v82, s18, v[12:13]
	v_mad_u64_u32 v[44:45], s[38:39], v81, s18, v[12:13]
	v_mad_u64_u32 v[46:47], s[38:39], v84, s18, v[12:13]
	v_mad_u64_u32 v[64:65], s[38:39], v83, s18, v[12:13]
	v_mad_u64_u32 v[66:67], s[38:39], v86, s18, v[12:13]
	v_mad_u64_u32 v[68:69], s[38:39], v85, s18, v[12:13]
	v_mad_u64_u32 v[70:71], s[38:39], v88, s18, v[12:13]
	v_mad_u64_u32 v[72:73], s[38:39], v87, s18, v[12:13]
	v_mad_u64_u32 v[74:75], s[38:39], v90, s18, v[12:13]
	v_mad_u64_u32 v[76:77], s[38:39], v89, s18, v[12:13]
	s_add_i32 s15, s15, 16
	s_add_i32 s13, s13, 16
	s_lshl_b32 s37, s13, 1
	s_lshl_b32 s38, s15, 1
	v_or_b32_e32 v174, s37, v1
	v_or_b32_e32 v175, s38, v2
	s_add_i32 s39, s37, 4
	s_add_i32 s40, s38, 4
	s_add_i32 s41, s37, 8
	s_add_i32 s42, s38, 8
	s_add_i32 s43, s37, 12
	s_add_i32 s44, s38, 12
	s_add_i32 s45, s37, 16
	s_add_i32 s46, s38, 16
	s_add_i32 s47, s37, 20
	s_add_i32 s48, s38, 20
	s_add_i32 s49, s37, 24
	s_add_i32 s50, s38, 24
	s_add_i32 s37, s37, 28
	s_add_i32 s38, s38, 28
	v_add_u32_e32 v110, s14, v175
	v_or_b32_e32 v129, s39, v1
	v_or_b32_e32 v144, s40, v2
	v_or_b32_e32 v145, s41, v1
	v_or_b32_e32 v146, s42, v2
	v_or_b32_e32 v147, s43, v1
	v_or_b32_e32 v148, s44, v2
	v_or_b32_e32 v149, s45, v1
	v_or_b32_e32 v150, s46, v2
	v_or_b32_e32 v151, s47, v1
	v_or_b32_e32 v152, s48, v2
	v_or_b32_e32 v153, s49, v1
	v_or_b32_e32 v154, s50, v2
	v_or_b32_e32 v155, s37, v1
	v_or_b32_e32 v156, s38, v2
	v_add_u32_e32 v112, s3, v174
	v_mad_i64_i32 v[110:111], s[38:39], v110, s35, v[28:29]
	v_add_u32_e32 v116, s3, v129
	v_add_u32_e32 v114, s14, v144
	v_add_u32_e32 v120, s3, v145
	v_add_u32_e32 v118, s14, v146
	v_add_u32_e32 v124, s3, v147
	v_add_u32_e32 v122, s14, v148
	v_add_u32_e32 v130, s3, v149
	v_add_u32_e32 v126, s14, v150
	v_add_u32_e32 v134, s3, v151
	v_add_u32_e32 v132, s14, v152
	v_add_u32_e32 v138, s3, v153
	v_add_u32_e32 v136, s14, v154
	v_add_u32_e32 v142, s3, v155
	v_add_u32_e32 v140, s14, v156
; #define LAS __attribute__((address_space(3)))
; __device__ __forceinline__ unsigned cvt_pk(float lo, float hi) { f32x2_t v = {lo, hi}; bf16x2_t b = __builtin_convertvector(v, bf16x2_t); return __builtin_bit_cast(unsigned, b); }
; __device__ __forceinline__ void transpose_item(const float* __restrict__ W, int ld_src, int k0, int n0src, const float* __restrict__ kscale, bf16_t* __restrict__ WT, int ldt, int n0dst, LAS float* scr, int lane) {
; #pragma unroll 8
;     for (int i = 0; i < 32; ++i) { const int kk = 2 * i + (lane >> 5); float v = W[(size_t)(k0 + kk) * ld_src + n0src + (lane & 31)]; if (kscale) v *= kscale[k0 + kk]; scr[kk * 33 + (lane & 31)] = v; }
;     asm volatile("s_waitcnt lgkmcnt(0)" ::: "memory"); __builtin_amdgcn_wave_barrier();
;     const int c = lane & 7;
; #pragma unroll
;     for (int jn = 0; jn < 4; ++jn) { const int n = (lane >> 3) + 8 * jn; const LAS float* s = scr + (8 * c) * 33 + n;
;         u32x4 o; o.x = cvt_pk(s[0 * 33], s[1 * 33]); o.y = cvt_pk(s[2 * 33], s[3 * 33]); o.z = cvt_pk(s[4 * 33], s[5 * 33]); o.w = cvt_pk(s[6 * 33], s[7 * 33]);
;         *(u32x4*)(WT + (size_t)(n0dst + n) * ldt + k0 + 8 * c) = o; }
	v_mad_i64_i32 v[112:113], s[38:39], v112, s35, v[28:29]
	v_mad_i64_i32 v[114:115], s[38:39], v114, s35, v[28:29]
	v_mad_i64_i32 v[116:117], s[38:39], v116, s35, v[28:29]
	v_mad_i64_i32 v[118:119], s[38:39], v118, s35, v[28:29]
	v_mad_i64_i32 v[120:121], s[38:39], v120, s35, v[28:29]
	v_mad_i64_i32 v[122:123], s[38:39], v122, s35, v[28:29]
	v_mad_i64_i32 v[124:125], s[38:39], v124, s35, v[28:29]
	v_mad_i64_i32 v[126:127], s[38:39], v126, s35, v[28:29]
	v_mad_i64_i32 v[130:131], s[38:39], v130, s35, v[28:29]
	v_mad_i64_i32 v[132:133], s[38:39], v132, s35, v[28:29]
	v_mad_i64_i32 v[134:135], s[38:39], v134, s35, v[28:29]
	v_mad_i64_i32 v[136:137], s[38:39], v136, s35, v[28:29]
	v_mad_i64_i32 v[138:139], s[38:39], v138, s35, v[28:29]
	v_mad_i64_i32 v[140:141], s[38:39], v140, s35, v[28:29]
	v_mad_i64_i32 v[142:143], s[38:39], v142, s35, v[28:29]
	global_load_dword v157, v[110:111], off
	global_load_dword v158, v[112:113], off
	global_load_dword v159, v[114:115], off
	global_load_dword v160, v[116:117], off
	global_load_dword v161, v[118:119], off
	global_load_dword v162, v[120:121], off
	global_load_dword v163, v[122:123], off
	global_load_dword v164, v[124:125], off
	global_load_dword v165, v[126:127], off
	global_load_dword v166, v[130:131], off
	global_load_dword v167, v[132:133], off
	global_load_dword v168, v[134:135], off
	global_load_dword v169, v[136:137], off
	global_load_dword v170, v[138:139], off
	global_load_dword v171, v[140:141], off
	global_load_dword v172, v[142:143], off
	v_mad_u64_u32 v[110:111], s[38:39], v175, s18, v[12:13]
	v_mad_u64_u32 v[112:113], s[38:39], v174, s18, v[12:13]
	v_mad_u64_u32 v[114:115], s[38:39], v144, s18, v[12:13]
	v_mad_u64_u32 v[116:117], s[38:39], v129, s18, v[12:13]
	v_mad_u64_u32 v[118:119], s[38:39], v146, s18, v[12:13]
	v_mad_u64_u32 v[120:121], s[38:39], v145, s18, v[12:13]
	v_mad_u64_u32 v[122:123], s[38:39], v148, s18, v[12:13]
	v_mad_u64_u32 v[124:125], s[38:39], v147, s18, v[12:13]
	v_mad_u64_u32 v[126:127], s[38:39], v150, s18, v[12:13]
	v_mad_u64_u32 v[130:131], s[38:39], v149, s18, v[12:13]
	v_mad_u64_u32 v[132:133], s[38:39], v152, s18, v[12:13]
	v_mad_u64_u32 v[134:135], s[38:39], v151, s18, v[12:13]
	v_mad_u64_u32 v[136:137], s[38:39], v154, s18, v[12:13]
	v_mad_u64_u32 v[138:139], s[38:39], v153, s18, v[12:13]
	v_mad_u64_u32 v[140:141], s[38:39], v156, s18, v[12:13]
	v_mad_u64_u32 v[142:143], s[38:39], v155, s18, v[12:13]
	s_waitcnt vmcnt(31)
	ds_write_b32 v30, v91
	s_waitcnt vmcnt(30)
	ds_write_b32 v32, v92
	s_waitcnt vmcnt(29)
	ds_write_b32 v34, v93
	s_waitcnt vmcnt(28)
	ds_write_b32 v36, v94
	s_waitcnt vmcnt(27)
	ds_write_b32 v38, v95
	s_waitcnt vmcnt(26)
	ds_write_b32 v40, v96
	s_waitcnt vmcnt(25)
	ds_write_b32 v42, v97
	s_waitcnt vmcnt(24)
	ds_write_b32 v44, v98
	s_waitcnt vmcnt(23)
	ds_write_b32 v46, v99
	s_waitcnt vmcnt(22)
	ds_write_b32 v64, v100
	s_waitcnt vmcnt(21)
	ds_write_b32 v66, v101
	s_waitcnt vmcnt(20)
	ds_write_b32 v68, v102
	s_waitcnt vmcnt(19)
	ds_write_b32 v70, v103
	s_waitcnt vmcnt(18)
	ds_write_b32 v72, v104
	s_waitcnt vmcnt(17)
	ds_write_b32 v74, v105
	s_waitcnt vmcnt(16)
	ds_write_b32 v76, v106
	s_waitcnt vmcnt(15)
	ds_write_b32 v110, v157
	s_waitcnt vmcnt(14)
	ds_write_b32 v112, v158
	s_waitcnt vmcnt(13)
	ds_write_b32 v114, v159
	s_waitcnt vmcnt(12)
	ds_write_b32 v116, v160
	s_waitcnt vmcnt(11)
	ds_write_b32 v118, v161
	s_waitcnt vmcnt(10)
	ds_write_b32 v120, v162
	s_waitcnt vmcnt(9)
	ds_write_b32 v122, v163
	s_waitcnt vmcnt(8)
	ds_write_b32 v124, v164
	s_waitcnt vmcnt(7)
	ds_write_b32 v126, v165
	s_waitcnt vmcnt(6)
	ds_write_b32 v130, v166
	s_waitcnt vmcnt(5)
	ds_write_b32 v132, v167
	s_waitcnt vmcnt(4)
	ds_write_b32 v134, v168
	s_waitcnt vmcnt(3)
	ds_write_b32 v136, v169
	s_waitcnt vmcnt(2)
	ds_write_b32 v138, v170
	s_waitcnt vmcnt(1)
	ds_write_b32 v140, v171
	s_waitcnt vmcnt(0)
	ds_write_b32 v142, v172
	s_mul_hi_i32 s3, s12, 0x3800000
	s_mul_i32 s12, s12, 0x3800000
	s_add_u32 s12, s6, s12
	s_addc_u32 s13, s7, s3
	s_add_i32 s3, s2, 0xc0
	s_cmpk_lt_i32 s0, 0x9a
	s_cselect_b32 s0, s2, s3
	s_waitcnt lgkmcnt(0)
	s_ashr_i32 s15, s14, 31
	ds_read2_b32 v[32:33], v7 offset0:33 offset1:41
	ds_read2_b32 v[34:35], v7 offset1:8
	ds_read2_b32 v[36:37], v7 offset0:66 offset1:74
	ds_read2_b32 v[38:39], v7 offset0:99 offset1:107
	ds_read2_b32 v[40:41], v7 offset0:132 offset1:140
	ds_read2_b32 v[42:43], v7 offset0:165 offset1:173
	ds_read2_b32 v[44:45], v7 offset0:198 offset1:206
	ds_read2_b32 v[46:47], v7 offset0:231 offset1:239
	s_lshl_b64 s[2:3], s[14:15], 1
	s_add_u32 s2, s12, s2
	v_or_b32_e32 v66, s0, v3
	s_addc_u32 s3, s13, s3
	v_lshlrev_b32_e32 v4, 1, v14
	v_ashrrev_i32_e32 v67, 31, v66
	v_lshl_add_u64 v[64:65], s[2:3], 0, v[4:5]
	v_lshlrev_b64 v[66:67], 12, v[66:67]
	s_waitcnt lgkmcnt(6)
	v_cvt_pk_bf16_f32 v28, v34, v32
	s_waitcnt lgkmcnt(4)
	v_cvt_pk_bf16_f32 v29, v36, v38
	s_waitcnt lgkmcnt(2)
	v_cvt_pk_bf16_f32 v30, v40, v42
	s_waitcnt lgkmcnt(0)
	v_cvt_pk_bf16_f32 v31, v44, v46
	v_lshl_add_u64 v[66:67], v[64:65], 0, v[66:67]
	v_or_b32_e32 v32, s0, v9
	global_store_dwordx4 v[66:67], v[28:31], off
	v_readlane_b32 s40, v254, 34
	v_readlane_b32 s41, v254, 35
	v_cvt_pk_bf16_f32 v28, v35, v33
	v_ashrrev_i32_e32 v33, 31, v32
	v_cvt_pk_bf16_f32 v29, v37, v39
	v_cvt_pk_bf16_f32 v30, v41, v43
	v_cvt_pk_bf16_f32 v31, v45, v47
	v_lshlrev_b64 v[32:33], 12, v[32:33]
	ds_read2_b32 v[34:35], v7 offset0:49 offset1:57
	ds_read2_b32 v[36:37], v7 offset0:16 offset1:24
	ds_read2_b32 v[38:39], v7 offset0:82 offset1:90
	ds_read2_b32 v[40:41], v7 offset0:115 offset1:123
	ds_read2_b32 v[42:43], v7 offset0:148 offset1:156
	ds_read2_b32 v[44:45], v7 offset0:181 offset1:189
	ds_read2_b32 v[46:47], v7 offset0:214 offset1:222
	ds_read2_b32 v[66:67], v7 offset0:247 offset1:255
	v_lshl_add_u64 v[32:33], v[64:65], 0, v[32:33]
	global_store_dwordx4 v[32:33], v[28:31], off
	v_or_b32_e32 v32, s0, v11
	v_ashrrev_i32_e32 v33, 31, v32
	v_lshlrev_b64 v[32:33], 12, v[32:33]
	s_waitcnt lgkmcnt(6)
	v_cvt_pk_bf16_f32 v28, v36, v34
	s_waitcnt lgkmcnt(4)
	v_cvt_pk_bf16_f32 v29, v38, v40
	s_waitcnt lgkmcnt(2)
	v_cvt_pk_bf16_f32 v30, v42, v44
	s_waitcnt lgkmcnt(0)
	v_cvt_pk_bf16_f32 v31, v46, v66
	v_lshl_add_u64 v[32:33], v[64:65], 0, v[32:33]
	global_store_dwordx4 v[32:33], v[28:31], off
	v_or_b32_e32 v32, s0, v13
	v_ashrrev_i32_e32 v33, 31, v32
	v_lshlrev_b64 v[32:33], 12, v[32:33]
	v_cvt_pk_bf16_f32 v28, v37, v35
	v_cvt_pk_bf16_f32 v29, v39, v41
	v_cvt_pk_bf16_f32 v30, v43, v45
	v_cvt_pk_bf16_f32 v31, v47, v67
	v_lshl_add_u64 v[32:33], v[64:65], 0, v[32:33]
	global_store_dwordx4 v[32:33], v[28:31], off
	s_waitcnt lgkmcnt(0)
	v_readlane_b32 s42, v254, 36
	v_readlane_b32 s43, v254, 37
	v_readlane_b32 s44, v254, 38
	v_readlane_b32 s45, v254, 39
	v_readlane_b32 s46, v254, 40
	v_readlane_b32 s47, v254, 41
	v_readlane_b32 s48, v254, 42
	v_readlane_b32 s49, v254, 43
	v_readlane_b32 s50, v254, 44
	v_readlane_b32 s51, v254, 45
	v_readlane_b32 s52, v254, 46
	v_readlane_b32 s53, v254, 47
	v_readlane_b32 s54, v254, 48
	v_readlane_b32 s55, v254, 49
	s_branch .LBB0_7
